# plus: layer-0 norm pass loads all 12 gain/scale/shift vectors per row up front with counted waits; header no longer waits for store acks
# baseline (speedup 1.0000x reference)
; DI void phase_norm(const Params& p, int layer, int which, const float* xsrc, const float* csrc, int nrows, int wv) {
;     ...
;   int row = blockIdx.x * 8 + w;
;   float4 nv[4];
;   if (row < nrows) {
;     const float* src = (row < NX) ? xsrc + (size_t)row * 1024 : csrc + (size_t)(row - NX) * 1024;
; #pragma unroll
;     for (int i = 0; i < 4; ++i) nv[i] = *(const float4*)(src + (lane + 64 * i) * 4);
;   }
;   for (; row < nrows; row += rstride) {
;     const int mrow = (row < NX) ? (row >> 11) : 32;
;     const float* mv = modv + (size_t)mrow * 6144;
;     float4 v[4]; float ss = 0.f;
; #pragma unroll
;     for (int i = 0; i < 4; ++i) { v[i] = nv[i]; ss += v[i].x * v[i].x + v[i].y * v[i].y + v[i].z * v[i].z + v[i].w * v[i].w; }
;     const int nrow = row + rstride;
;     if (nrow < nrows) {
;       const float* src = (nrow < NX) ? xsrc + (size_t)nrow * 1024 : csrc + (size_t)(nrow - NX) * 1024;
; #pragma unroll
;       for (int i = 0; i < 4; ++i) nv[i] = *(const float4*)(src + (lane + 64 * i) * 4);
;     }
;     ss = wave_sum(ss, lane);
;     const float rinv = rsqrtf(ss * (1.f / 1024.f) + 1e-6f);
; #pragma unroll
;     for (int i = 0; i < 4; ++i) {
;       const int col = (lane + 64 * i) * 4;
;       float4 gg = *(const float4*)(g + col), sc = *(const float4*)(mv + scc + col), sh = *(const float4*)(mv + shc + col);
;       float y0 = v[i].x * rinv * gg.x * (1.f + sc.x) + sh.x, y1 = v[i].y * rinv * gg.y * (1.f + sc.y) + sh.y;
;       float y2 = v[i].z * rinv * gg.z * (1.f + sc.z) + sh.z, y3 = v[i].w * rinv * gg.w * (1.f + sc.w) + sh.w;
;       uint2 o; o.x = pack2(y0, y1); o.y = pack2(y2, y3);
;       *(uint2*)(H + (size_t)row * 1024 + col) = o;
.LBB0_157:
	s_or_b64 exec, exec, s[4:5]
	v_mbcnt_lo_u32_b32 v16, -1, 0
	v_mbcnt_hi_u32_b32 v16, -1, v16
	s_mov_b32 s17, 0x12000
	v_add_u32_e32 v0, s53, v16
	v_ashrrev_i32_e32 v0, 6, v0
	v_lshl_add_u32 v32, s68, 3, v0
	v_cmp_gt_i32_e32 vcc, s17, v32
	s_and_saveexec_b64 s[4:5], vcc
	s_cbranch_execz .LBB0_162
	v_readlane_b32 s36, v251, 26
	s_mov_b32 s18, 0x10000
	v_readlane_b32 s37, v251, 27
	v_readlane_b32 s41, v251, 31
	v_add_u32_e32 v0, 0xffff0000, v32
	v_ashrrev_i32_e32 v33, 31, v32
	v_cmp_gt_i32_e32 vcc, s18, v32
	v_readlane_b32 s40, v251, 30
	v_mov_b32_e32 v2, s41
	v_mov_b32_e32 v3, s37
	v_cndmask_b32_e32 v1, 0, v33, vcc
	v_cndmask_b32_e32 v0, v0, v32, vcc
	v_cndmask_b32_e32 v3, v2, v3, vcc
	v_mov_b32_e32 v2, s40
	v_mov_b32_e32 v4, s36
	v_lshlrev_b32_e32 v17, 2, v16
	v_cndmask_b32_e32 v2, v2, v4, vcc
	v_lshlrev_b64 v[0:1], 12, v[0:1]
	v_and_b32_e32 v36, 0xfc, v17
	v_mov_b32_e32 v35, 0
	v_lshl_add_u64 v[0:1], v[2:3], 0, v[0:1]
	v_lshlrev_b32_e32 v34, 2, v36
	v_lshl_add_u64 v[0:1], v[0:1], 0, v[34:35]
	global_load_dwordx4 v[12:15], v[0:1], off
	global_load_dwordx4 v[8:11], v[0:1], off offset:1024
	global_load_dwordx4 v[4:7], v[0:1], off offset:2048
	s_nop 0
	global_load_dwordx4 v[0:3], v[0:1], off offset:3072
	v_lshlrev_b64 v[24:25], 11, v[32:33]
	v_and_b32_e32 v16, 63, v16
	s_lshl_b32 s6, s34, 3
	s_movk_i32 s7, 0x80
	v_bfrev_b32_e32 v18, 0.5
	v_lshl_or_b32 v24, v16, 3, v24
	v_readlane_b32 s44, v251, 34
	v_readlane_b32 s45, v251, 35
	v_bitop3_b32 v37, v17, s7, v18 bitop3:0x6c
	v_bitop3_b32 v50, v17, 64, v18 bitop3:0x6c
	v_bitop3_b32 v51, v17, 32, v18 bitop3:0x6c
	v_bitop3_b32 v52, v17, 16, v18 bitop3:0x6c
	v_bitop3_b32 v53, v17, 8, v18 bitop3:0x6c
	v_bitop3_b32 v54, v17, 4, v18 bitop3:0x6c
	v_or_b32_e32 v18, 0x100, v36
	v_or_b32_e32 v20, 0x200, v36
	v_or_b32_e32 v22, 0x300, v36
	v_lshl_add_u64 v[16:17], s[62:63], 0, v[24:25]
	s_mov_b64 s[8:9], 0x9000000
	s_ashr_i32 s7, s6, 31
	v_add_u32_e32 v42, s6, v32
	v_lshl_add_u64 v[38:39], s[44:45], 0, v[34:35]
	v_lshl_add_u64 v[40:41], v[16:17], 0, s[8:9]
	s_lshl_b64 s[8:9], s[6:7], 11
	v_ashrrev_i32_e32 v43, 31, v42
	s_mov_b64 s[10:11], 0
	v_mov_b32_e32 v33, 0x358637bd
	s_mov_b32 s19, 0x800000
	s_mov_b64 s[12:13], 0x1000
	v_lshlrev_b32_e32 v44, 2, v18
	v_lshlrev_b32_e32 v46, 2, v20
	v_lshlrev_b32_e32 v48, 2, v22
	s_mov_b32 s20, 0x11fff
	v_readlane_b32 s38, v251, 28
	v_readlane_b32 s39, v251, 29
	v_readlane_b32 s42, v251, 32
	v_readlane_b32 s43, v251, 33
	v_readlane_b32 s46, v251, 36
	v_readlane_b32 s47, v251, 37
	v_readlane_b32 s48, v251, 38
	v_readlane_b32 s49, v251, 39
	v_readlane_b32 s50, v251, 40
	v_readlane_b32 s51, v251, 41
	s_waitcnt vmcnt(0)
	s_branch .LBB0_160
.LBB0_159:
	s_or_b64 exec, exec, s[14:15]
	v_min_i32_e32 v45, 0x10000, v32
	v_ashrrev_i32_e32 v45, 11, v45
	v_readlane_b32 s14, v251, 60
	v_mul_hi_i32_i24_e32 v57, 0x6000, v45
	v_mul_i32_i24_e32 v56, 0x6000, v45
	v_readlane_b32 s15, v251, 61
	v_pk_mul_f32 v[72:73], v[12:13], v[12:13]
	v_pk_mul_f32 v[76:77], v[8:9], v[8:9]
	v_lshl_add_u64 v[64:65], s[14:15], 0, v[56:57]
	v_lshl_add_u64 v[68:69], v[64:65], 0, s[12:13]
	v_lshl_add_u64 v[60:61], v[68:69], 0, v[34:35]
	global_load_dwordx4 v[56:59], v[38:39], off
	v_lshl_add_u64 v[70:71], v[64:65], 0, v[34:35]
	global_load_dwordx4 v[60:63], v[60:61], off
	v_pk_mul_f32 v[74:75], v[14:15], v[14:15]
	global_load_dwordx4 v[64:67], v[70:71], off
	v_mov_b32_e32 v136, v44
	v_mov_b32_e32 v137, v35
	v_mov_b32_e32 v138, v46
	v_mov_b32_e32 v139, v35
	v_mov_b32_e32 v140, v48
	v_mov_b32_e32 v141, v35
	v_lshl_add_u64 v[136:137], v[68:69], 0, v[136:137]
	v_lshl_add_u64 v[138:139], v[68:69], 0, v[138:139]
	v_lshl_add_u64 v[140:141], v[68:69], 0, v[140:141]
	global_load_dwordx4 v[100:103], v[38:39], off offset:1024
	global_load_dwordx4 v[104:107], v[136:137], off
	global_load_dwordx4 v[108:111], v[70:71], off offset:1024
	global_load_dwordx4 v[112:115], v[38:39], off offset:2048
	global_load_dwordx4 v[116:119], v[138:139], off
	global_load_dwordx4 v[120:123], v[70:71], off offset:2048
	global_load_dwordx4 v[124:127], v[38:39], off offset:3072
	global_load_dwordx4 v[128:131], v[140:141], off
	global_load_dwordx4 v[132:135], v[70:71], off offset:3072
	v_pk_mul_f32 v[78:79], v[10:11], v[10:11]
	v_pk_mul_f32 v[80:81], v[4:5], v[4:5]
	v_add_f32_e32 v34, v76, v77
	v_add_f32_e32 v45, v72, v73
	v_pk_mul_f32 v[82:83], v[6:7], v[6:7]
	v_pk_mul_f32 v[84:85], v[0:1], v[0:1]
	v_add_f32_e32 v47, v80, v81
	v_add_f32_e32 v34, v34, v78
	v_add_f32_e32 v45, v45, v74
	v_pk_mul_f32 v[86:87], v[2:3], v[2:3]
	v_add_f32_e32 v49, v84, v85
	v_add_f32_e32 v47, v47, v82
	v_add_f32_e32 v34, v34, v79
	v_add_f32_e32 v45, v45, v75
	v_add_f32_e32 v49, v49, v86
	v_add_f32_e32 v47, v47, v83
	v_add_f32_e32 v34, v45, v34
	v_add_f32_e32 v49, v49, v87
	v_add_f32_e32 v34, v34, v47
	v_add_f32_e32 v34, v34, v49
	ds_bpermute_b32 v45, v37, v34
	v_mov_b32_e32 v47, v35
	v_mov_b32_e32 v49, v35
	v_add_u32_e32 v32, s6, v32
	v_lshl_add_u64 v[42:43], v[42:43], 0, s[6:7]
	s_waitcnt lgkmcnt(0)
	v_add_f32_e32 v34, v34, v45
	ds_bpermute_b32 v45, v50, v34
	s_waitcnt lgkmcnt(0)
	v_add_f32_e32 v34, v34, v45
	ds_bpermute_b32 v45, v51, v34
	s_waitcnt lgkmcnt(0)
; DI void phase_norm(const Params& p, int layer, int which, const float* xsrc, const float* csrc, int nrows, int wv) {
;     ...
;   for (; row < nrows; row += rstride) {
;     const int mrow = (row < NX) ? (row >> 11) : 32;
;     const float* mv = modv + (size_t)mrow * 6144;
;     float4 v[4]; float ss = 0.f;
; #pragma unroll
;     for (int i = 0; i < 4; ++i) { v[i] = nv[i]; ss += v[i].x * v[i].x + v[i].y * v[i].y + v[i].z * v[i].z + v[i].w * v[i].w; }
;     const int nrow = row + rstride;
;     if (nrow < nrows) {
;       const float* src = (nrow < NX) ? xsrc + (size_t)nrow * 1024 : csrc + (size_t)(nrow - NX) * 1024;
; #pragma unroll
;       for (int i = 0; i < 4; ++i) nv[i] = *(const float4*)(src + (lane + 64 * i) * 4);
;     }
;     ss = wave_sum(ss, lane);
;     const float rinv = rsqrtf(ss * (1.f / 1024.f) + 1e-6f);
; #pragma unroll
;     for (int i = 0; i < 4; ++i) {
;       const int col = (lane + 64 * i) * 4;
;       float4 gg = *(const float4*)(g + col), sc = *(const float4*)(mv + scc + col), sh = *(const float4*)(mv + shc + col);
;       float y0 = v[i].x * rinv * gg.x * (1.f + sc.x) + sh.x, y1 = v[i].y * rinv * gg.y * (1.f + sc.y) + sh.y;
;       float y2 = v[i].z * rinv * gg.z * (1.f + sc.z) + sh.z, y3 = v[i].w * rinv * gg.w * (1.f + sc.w) + sh.w;
;       uint2 o; o.x = pack2(y0, y1); o.y = pack2(y2, y3);
;       *(uint2*)(H + (size_t)row * 1024 + col) = o;
;     }
;   }
	v_add_f32_e32 v34, v34, v45
	ds_bpermute_b32 v45, v52, v34
	s_waitcnt lgkmcnt(0)
	v_add_f32_e32 v34, v34, v45
	ds_bpermute_b32 v45, v53, v34
	s_waitcnt lgkmcnt(0)
	v_add_f32_e32 v34, v34, v45
	ds_bpermute_b32 v45, v54, v34
	s_waitcnt lgkmcnt(0)
	v_add_f32_e32 v34, v34, v45
	v_fmamk_f32 v34, v34, 0x3a800000, v33
	v_mul_f32_e32 v45, 0x4b800000, v34
	v_cmp_gt_f32_e32 vcc, s19, v34
	s_nop 1
	v_cndmask_b32_e32 v34, v34, v45, vcc
	v_rsq_f32_e32 v34, v34
	v_mov_b32_e32 v45, v35
	v_lshl_add_u64 v[72:73], v[68:69], 0, v[44:45]
	v_mul_f32_e32 v45, 0x45800000, v34
	v_cndmask_b32_e32 v34, v34, v45, vcc
	v_pk_mul_f32 v[12:13], v[12:13], v[34:35] op_sel_hi:[1,0]
	v_pk_mul_f32 v[14:15], v[14:15], v[34:35] op_sel_hi:[1,0]
	v_pk_mul_f32 v[8:9], v[8:9], v[34:35] op_sel_hi:[1,0]
	v_pk_mul_f32 v[10:11], v[10:11], v[34:35] op_sel_hi:[1,0]
	v_pk_mul_f32 v[4:5], v[4:5], v[34:35] op_sel_hi:[1,0]
	v_pk_mul_f32 v[6:7], v[6:7], v[34:35] op_sel_hi:[1,0]
	v_pk_mul_f32 v[2:3], v[2:3], v[34:35] op_sel_hi:[1,0]
	s_waitcnt vmcnt(11)
	v_pk_mul_f32 v[12:13], v[56:57], v[12:13]
	v_pk_mul_f32 v[14:15], v[58:59], v[14:15]
	s_waitcnt vmcnt(10)
	v_pk_add_f32 v[56:57], v[60:61], 1.0 op_sel_hi:[1,0]
	v_pk_add_f32 v[58:59], v[62:63], 1.0 op_sel_hi:[1,0]
	s_waitcnt vmcnt(9)
	v_pk_fma_f32 v[12:13], v[56:57], v[12:13], v[64:65]
	v_pk_fma_f32 v[14:15], v[58:59], v[14:15], v[66:67]
	v_cvt_pk_bf16_f32 v12, v12, v13
	v_cvt_pk_bf16_f32 v13, v14, v15
	global_store_dwordx2 v[40:41], v[12:13], off
	v_lshl_add_u64 v[64:65], v[68:69], 0, v[46:47]
	v_cmp_lt_i32_e32 vcc, s20, v32
	s_or_b64 s[10:11], vcc, s[10:11]
	s_waitcnt vmcnt(9)
	v_pk_mul_f32 v[8:9], v[8:9], v[100:101]
	s_waitcnt vmcnt(8)
	v_pk_add_f32 v[12:13], v[104:105], 1.0 op_sel_hi:[1,0]
	v_pk_mul_f32 v[10:11], v[10:11], v[102:103]
	v_pk_add_f32 v[14:15], v[106:107], 1.0 op_sel_hi:[1,0]
	s_waitcnt vmcnt(7)
	v_pk_fma_f32 v[8:9], v[8:9], v[12:13], v[108:109]
	v_pk_fma_f32 v[10:11], v[10:11], v[14:15], v[110:111]
	v_cvt_pk_bf16_f32 v8, v8, v9
	v_cvt_pk_bf16_f32 v9, v10, v11
	global_store_dwordx2 v[40:41], v[8:9], off offset:512
	v_lshl_add_u64 v[60:61], v[68:69], 0, v[48:49]
	v_pk_mul_f32 v[68:69], v[0:1], v[34:35] op_sel_hi:[1,0]
	v_mov_b64_e32 v[0:1], v[24:25]
	s_waitcnt vmcnt(7)
	v_pk_mul_f32 v[4:5], v[4:5], v[112:113]
	s_waitcnt vmcnt(6)
	v_pk_add_f32 v[8:9], v[116:117], 1.0 op_sel_hi:[1,0]
	v_pk_mul_f32 v[6:7], v[6:7], v[114:115]
	v_pk_add_f32 v[10:11], v[118:119], 1.0 op_sel_hi:[1,0]
	s_waitcnt vmcnt(5)
	v_pk_fma_f32 v[4:5], v[4:5], v[8:9], v[120:121]
	v_pk_fma_f32 v[6:7], v[6:7], v[10:11], v[122:123]
	v_cvt_pk_bf16_f32 v4, v4, v5
	v_cvt_pk_bf16_f32 v5, v6, v7
	global_store_dwordx2 v[40:41], v[4:5], off offset:1024
	v_mov_b64_e32 v[12:13], v[16:17]
	v_mov_b64_e32 v[14:15], v[18:19]
	v_mov_b64_e32 v[8:9], v[20:21]
	v_mov_b64_e32 v[10:11], v[22:23]
	v_mov_b64_e32 v[4:5], v[28:29]
	v_mov_b64_e32 v[6:7], v[30:31]
	s_waitcnt vmcnt(5)
	v_pk_mul_f32 v[16:17], v[68:69], v[124:125]
	s_waitcnt vmcnt(4)
	v_pk_add_f32 v[18:19], v[128:129], 1.0 op_sel_hi:[1,0]
	v_pk_mul_f32 v[2:3], v[2:3], v[126:127]
	v_pk_add_f32 v[20:21], v[130:131], 1.0 op_sel_hi:[1,0]
	s_waitcnt vmcnt(3)
	v_pk_fma_f32 v[16:17], v[16:17], v[18:19], v[132:133]
	v_pk_fma_f32 v[2:3], v[2:3], v[20:21], v[134:135]
	v_cvt_pk_bf16_f32 v16, v16, v17
	v_cvt_pk_bf16_f32 v17, v2, v3
	global_store_dwordx2 v[40:41], v[16:17], off offset:1536
	v_lshl_add_u64 v[40:41], v[40:41], 0, s[8:9]
	v_mov_b64_e32 v[2:3], v[26:27]
	s_andn2_b64 exec, exec, s[10:11]
	s_cbranch_execz .LBB0_162
.LBB0_160:
	v_cmp_gt_i32_e32 vcc, s17, v42
	v_lshlrev_b32_e32 v34, 2, v36
	s_nop 0
	v_mov_b64_e32 v[16:17], v[12:13]
	v_mov_b64_e32 v[18:19], v[14:15]
	s_nop 0
	v_mov_b64_e32 v[20:21], v[8:9]
	v_mov_b64_e32 v[22:23], v[10:11]
	s_nop 0
	v_mov_b64_e32 v[28:29], v[4:5]
	v_mov_b64_e32 v[30:31], v[6:7]
	s_nop 0
	v_mov_b64_e32 v[24:25], v[0:1]
	v_mov_b64_e32 v[26:27], v[2:3]
	s_and_saveexec_b64 s[14:15], vcc
	s_cbranch_execz .LBB0_159
	v_readlane_b32 s36, v251, 26
	v_readlane_b32 s37, v251, 27
	v_readlane_b32 s41, v251, 31
	v_add_u32_e32 v16, 0xffff0000, v42
	v_cmp_gt_i32_e32 vcc, s18, v42
	v_readlane_b32 s40, v251, 30
	v_mov_b32_e32 v18, s41
	v_mov_b32_e32 v19, s37
	v_cndmask_b32_e32 v17, 0, v43, vcc
	v_cndmask_b32_e32 v16, v16, v42, vcc
	v_cndmask_b32_e32 v19, v18, v19, vcc
	v_mov_b32_e32 v18, s40
	v_mov_b32_e32 v20, s36
	v_cndmask_b32_e32 v18, v18, v20, vcc
	v_lshlrev_b64 v[16:17], 12, v[16:17]
	v_lshl_add_u64 v[16:17], v[18:19], 0, v[16:17]
	v_lshl_add_u64 v[24:25], v[16:17], 0, v[34:35]
	global_load_dwordx4 v[16:19], v[24:25], off
	global_load_dwordx4 v[20:23], v[24:25], off offset:1024
	global_load_dwordx4 v[28:31], v[24:25], off offset:2048
	s_nop 0
	global_load_dwordx4 v[24:27], v[24:25], off offset:3072
	v_readlane_b32 s38, v251, 28
	v_readlane_b32 s39, v251, 29
	v_readlane_b32 s42, v251, 32
	v_readlane_b32 s43, v251, 33
	v_readlane_b32 s44, v251, 34
	v_readlane_b32 s45, v251, 35
	v_readlane_b32 s46, v251, 36
	v_readlane_b32 s47, v251, 37
	v_readlane_b32 s48, v251, 38
	v_readlane_b32 s49, v251, 39
	v_readlane_b32 s50, v251, 40
	v_readlane_b32 s51, v251, 41
	s_branch .LBB0_159
